# static priority raise for waves 4-7 also during the m3 phase (compression MLP rows and SSD state pass), reset at the m4 entry
# baseline (speedup 1.0000x reference)
.LBB0_706:
	s_or_b64 exec, exec, s[6:7]
	v_mov_b32_e32 v20, v1
	s_mov_b64 s[4:5], s[0:1]
	s_barrier
	s_load_dwordx2 s[8:9], s[4:5], 0xd8
	v_readfirstlane_b32 s2, v20
	s_ashr_i32 s4, s2, 6
	s_cmp_ge_u32 s4, 4
	s_cbranch_scc0 .Lm3_prio_skip
	s_setprio 2
.Lm3_prio_skip:
	v_readlane_b32 s2, v243, 2
	s_add_i32 s2, s4, s2
	s_mov_b64 s[6:7], s[0:1]
	s_cmpk_gt_i32 s2, 0x7ff
	s_cbranch_scc1 .LBB0_727
	s_waitcnt lgkmcnt(0)
	s_add_u32 s10, s8, 0x15c00000
	s_load_dwordx2 s[6:7], s[6:7], 0x78
	s_addc_u32 s11, s9, 0
	s_add_u32 s12, s8, 0x15c80000
	s_addc_u32 s13, s9, 0
	v_and_b32_e32 v2, 63, v20
	v_lshlrev_b32_e32 v3, 1, v20
	s_add_u32 s20, s8, 0x15800610
	v_lshlrev_b32_e32 v10, 2, v2
	v_and_b32_e32 v24, 48, v3
	s_addc_u32 s21, s9, 0
	s_lshl_b32 s4, s4, 2
	v_readlane_b32 s5, v243, 22
	s_waitcnt lgkmcnt(0)
	v_lshl_add_u64 v[2:3], s[6:7], 0, v[10:11]
	v_bfe_u32 v21, v20, 4, 2
	v_and_b32_e32 v22, 15, v20
	v_bfe_u32 v23, v20, 5, 1
	v_and_b32_e32 v25, 7, v20
	s_add_i32 s14, s5, s4
	v_lshl_add_u64 v[12:13], v[2:3], 0, s[56:57]
	s_branch .LBB0_709

.LBB0_1254:
	s_setprio 0
	s_andn2_b64 vcc, exec, s[6:7]
	s_cbranch_vccnz .LBB0_2256
	s_mov_b64 s[4:5], s[0:1]
	s_load_dwordx2 s[90:91], s[4:5], 0xd8
	v_readfirstlane_b32 s2, v180
	s_ashr_i32 s2, s2, 6
	v_and_b32_e32 v181, 63, v180
	s_mul_i32 s18, s2, 0x4500
	v_or_b32_e32 v221, 0xffffffc0, v181
	v_lshlrev_b32_e32 v222, 2, v181
	s_add_i32 s96, s18, 0
	v_add_u32_e32 v2, s96, v222
	s_mov_b64 s[6:7], 0
	v_mov_b32_e32 v3, v221
